# EpiResid epilogue: second-half x loads issued (into the freed first-half x registers) before the first-half stores, so their wait no longer depends on the store acks
# baseline (speedup 1.0000x reference)
;     __device__ __forceinline__ void operator()(const f32x4 (&acc)[2][2][4][2], const pg8::Unit& u, int wr, int wc, int fr, int fq) const {
;         const int row0 = u.pm * 256 + wr * 64 + fr, col0 = u.pn * 256 + wc * 32 + 8 * fq;
;         const bool isctx = u.pm >= T / 256; const int mb = isctx ? 2 : (u.pm >> 6);
;         const float* xi = isctx ? xin_ctx - (size_t)T * D : xin_lat; float* xo = isctx ? xout_ctx - (size_t)T * D : xout_lat;
;         const float* gp = gate + mb * 9216 + col0;
;         f32x4 gv[2][2];
; #pragma unroll
;         for (int bj = 0; bj < 2; ++bj)
; #pragma unroll
;             for (int n = 0; n < 2; ++n) gv[bj][n] = *(const f32x4*)(gp + bj * 128 + n * 4) * coef;
; #pragma unroll
;         for (int ai = 0; ai < 2; ++ai) {
;             f32x4 xv[4][2][2];
; #pragma unroll
;             for (int m = 0; m < 4; ++m)
; #pragma unroll
;                 for (int bj = 0; bj < 2; ++bj)
; #pragma unroll
;                     for (int n = 0; n < 2; ++n) xv[m][bj][n] = *(const f32x4*)(xi + (size_t)(row0 + ai * 128 + m * 16) * D + col0 + bj * 128 + n * 4);
; #pragma unroll
;             for (int m = 0; m < 4; ++m)
; #pragma unroll
;                 for (int bj = 0; bj < 2; ++bj)
; #pragma unroll
;                     for (int n = 0; n < 2; ++n) *(f32x4*)(xo + (size_t)(row0 + ai * 128 + m * 16) * D + col0 + bj * 128 + n * 4) = xv[m][bj][n] + gv[bj][n] * acc[ai][bj][m][n];
.LBB0_586:
	s_lshr_b32 s24, s69, 6
	s_cmpk_gt_i32 s69, 0x7f
	s_mulk_i32 s24, 0x2400
	v_readlane_b32 s25, v250, 46
	s_cselect_b32 s24, 0x4800, s24
	s_cselect_b32 s28, s25, s90
	v_readlane_b32 s25, v250, 47
	s_cselect_b32 s26, s62, s46
	s_cselect_b32 s27, s63, s45
	s_cselect_b32 s29, s25, s91
	s_ashr_i32 s25, s24, 31
	v_lshl_or_b32 v132, s70, 8, v156
	s_lshl_b64 s[24:25], s[24:25], 2
	s_add_u32 s24, s47, s24
	v_ashrrev_i32_e32 v133, 31, v132
	s_addc_u32 s25, s48, s25
	v_lshlrev_b64 v[132:133], 2, v[132:133]
	v_lshl_add_u64 v[142:143], s[24:25], 0, v[132:133]
	global_load_dwordx4 v[134:137], v[142:143], off offset:16
	global_load_dwordx4 v[138:141], v[142:143], off
	global_load_dwordx4 v[158:161], v[142:143], off offset:528
	global_load_dwordx4 v[170:173], v[142:143], off offset:512
	v_lshl_add_u32 v152, s69, 8, v154
	v_ashrrev_i32_e32 v153, 31, v152
	v_lshlrev_b64 v[152:153], 12, v[152:153]
	v_lshl_add_u64 v[150:151], s[26:27], 0, v[132:133]
	v_lshl_add_u64 v[246:247], s[28:29], 0, v[132:133]
	v_lshl_add_u64 v[150:151], v[150:151], 0, v[152:153]
	v_lshl_add_u64 v[246:247], v[246:247], 0, v[152:153]
	global_load_dwordx4 v[174:177], v[150:151], off
	global_load_dwordx4 v[178:181], v[150:151], off offset:16
	global_load_dwordx4 v[186:189], v[150:151], off offset:512
	global_load_dwordx4 v[182:185], v[150:151], off offset:528
	s_mov_b64 s[24:25], 0x10000
	v_lshl_add_u64 v[152:153], v[150:151], 0, s[24:25]
	global_load_dwordx4 v[206:209], v[152:153], off
	global_load_dwordx4 v[210:213], v[152:153], off offset:16
	global_load_dwordx4 v[218:221], v[152:153], off offset:512
	global_load_dwordx4 v[214:217], v[152:153], off offset:528
	s_mov_b64 s[24:25], 0x20000
	v_lshl_add_u64 v[202:203], v[150:151], 0, s[24:25]
	global_load_dwordx4 v[222:225], v[202:203], off
	global_load_dwordx4 v[226:229], v[202:203], off offset:16
	global_load_dwordx4 v[230:233], v[202:203], off offset:512
	global_load_dwordx4 v[234:237], v[202:203], off offset:528
	s_mov_b64 s[24:25], 0x30000
	v_lshl_add_u64 v[152:153], v[150:151], 0, s[24:25]
	global_load_dwordx4 v[238:241], v[152:153], off
	global_load_dwordx4 v[242:245], v[152:153], off offset:16
	global_load_dwordx4 v[194:197], v[152:153], off offset:512
	global_load_dwordx4 v[164:167], v[152:153], off offset:528
	s_and_b64 vcc, exec, s[4:5]
	s_mov_b64 s[4:5], -1
	s_waitcnt vmcnt(0)
	v_pk_mul_f32 v[142:143], s[16:17], v[136:137]
	v_pk_mul_f32 v[146:147], s[16:17], v[140:141]
	v_pk_mul_f32 v[148:149], s[12:13], v[138:139]
	v_pk_mul_f32 v[144:145], s[12:13], v[134:135]
	v_pk_mul_f32 v[138:139], s[16:17], v[172:173]
	v_pk_mul_f32 v[140:141], s[12:13], v[170:171]
	v_pk_mul_f32 v[134:135], s[16:17], v[160:161]
	v_pk_mul_f32 v[136:137], s[12:13], v[158:159]
	v_pk_fma_f32 v[128:129], v[128:129], v[146:147], v[176:177]
	v_pk_fma_f32 v[126:127], v[126:127], v[148:149], v[174:175]
	v_pk_fma_f32 v[124:125], v[124:125], v[142:143], v[180:181]
	v_pk_fma_f32 v[122:123], v[122:123], v[144:145], v[178:179]
	v_pk_fma_f32 v[108:109], v[108:109], v[138:139], v[188:189]
	v_pk_fma_f32 v[106:107], v[106:107], v[140:141], v[186:187]
	v_pk_fma_f32 v[104:105], v[104:105], v[134:135], v[184:185]
	v_pk_fma_f32 v[102:103], v[102:103], v[136:137], v[182:183]
	v_pk_fma_f32 v[120:121], v[120:121], v[146:147], v[208:209]
	v_pk_fma_f32 v[118:119], v[118:119], v[148:149], v[206:207]
	v_pk_fma_f32 v[116:117], v[116:117], v[142:143], v[212:213]
	v_pk_fma_f32 v[114:115], v[114:115], v[144:145], v[210:211]
	v_pk_fma_f32 v[100:101], v[100:101], v[138:139], v[220:221]
	v_pk_fma_f32 v[98:99], v[98:99], v[140:141], v[218:219]
	v_pk_fma_f32 v[96:97], v[96:97], v[134:135], v[216:217]
	v_pk_fma_f32 v[94:95], v[94:95], v[136:137], v[214:215]
	v_pk_fma_f32 v[112:113], v[112:113], v[146:147], v[224:225]
	v_pk_fma_f32 v[110:111], v[110:111], v[148:149], v[222:223]
	v_pk_fma_f32 v[92:93], v[92:93], v[142:143], v[228:229]
	v_pk_fma_f32 v[90:91], v[90:91], v[144:145], v[226:227]
	v_pk_fma_f32 v[84:85], v[84:85], v[138:139], v[232:233]
	v_pk_fma_f32 v[82:83], v[82:83], v[140:141], v[230:231]
	v_pk_fma_f32 v[76:77], v[76:77], v[134:135], v[236:237]
	v_pk_fma_f32 v[74:75], v[74:75], v[136:137], v[234:235]
	v_pk_fma_f32 v[88:89], v[88:89], v[146:147], v[240:241]
	v_pk_fma_f32 v[86:87], v[86:87], v[148:149], v[238:239]
	v_pk_fma_f32 v[80:81], v[80:81], v[142:143], v[244:245]
	v_pk_fma_f32 v[78:79], v[78:79], v[144:145], v[242:243]
	v_pk_fma_f32 v[72:73], v[72:73], v[138:139], v[196:197]
	v_pk_fma_f32 v[70:71], v[70:71], v[140:141], v[194:195]
	v_pk_fma_f32 v[68:69], v[68:69], v[134:135], v[166:167]
	v_pk_fma_f32 v[66:67], v[66:67], v[136:137], v[164:165]
	s_mov_b64 s[24:25], 0x80000
	v_lshl_add_u64 v[202:203], v[150:151], 0, s[24:25]
	global_load_dwordx4 v[174:177], v[202:203], off
	global_load_dwordx4 v[178:181], v[202:203], off offset:16
	global_load_dwordx4 v[186:189], v[202:203], off offset:512
	global_load_dwordx4 v[182:185], v[202:203], off offset:528
	s_mov_b64 s[24:25], 0x90000
	v_lshl_add_u64 v[152:153], v[150:151], 0, s[24:25]
	global_load_dwordx4 v[206:209], v[152:153], off
	global_load_dwordx4 v[210:213], v[152:153], off offset:16
	global_load_dwordx4 v[218:221], v[152:153], off offset:512
	global_load_dwordx4 v[214:217], v[152:153], off offset:528
	s_mov_b64 s[24:25], 0xa0000
	v_lshl_add_u64 v[202:203], v[150:151], 0, s[24:25]
	global_load_dwordx4 v[222:225], v[202:203], off
	global_load_dwordx4 v[226:229], v[202:203], off offset:16
	global_load_dwordx4 v[230:233], v[202:203], off offset:512
	global_load_dwordx4 v[234:237], v[202:203], off offset:528
	s_mov_b64 s[24:25], 0xb0000
	v_lshl_add_u64 v[152:153], v[150:151], 0, s[24:25]
	global_load_dwordx4 v[238:241], v[152:153], off
	global_load_dwordx4 v[242:245], v[152:153], off offset:16
	global_load_dwordx4 v[194:197], v[152:153], off offset:512
	global_load_dwordx4 v[164:167], v[152:153], off offset:528
	global_store_dwordx4 v[246:247], v[126:129], off
	global_store_dwordx4 v[246:247], v[122:125], off offset:16
	global_store_dwordx4 v[246:247], v[106:109], off offset:512
	global_store_dwordx4 v[246:247], v[102:105], off offset:528
	s_mov_b64 s[24:25], 0x10000
	v_lshl_add_u64 v[204:205], v[246:247], 0, s[24:25]
	global_store_dwordx4 v[204:205], v[118:121], off
	global_store_dwordx4 v[204:205], v[114:117], off offset:16
	global_store_dwordx4 v[204:205], v[98:101], off offset:512
	global_store_dwordx4 v[204:205], v[94:97], off offset:528
	s_mov_b64 s[24:25], 0x20000
	v_lshl_add_u64 v[190:191], v[246:247], 0, s[24:25]
	global_store_dwordx4 v[190:191], v[110:113], off
	global_store_dwordx4 v[190:191], v[90:93], off offset:16
	global_store_dwordx4 v[190:191], v[82:85], off offset:512
	global_store_dwordx4 v[190:191], v[74:77], off offset:528
	s_mov_b64 s[24:25], 0x30000
	v_lshl_add_u64 v[204:205], v[246:247], 0, s[24:25]
	global_store_dwordx4 v[204:205], v[86:89], off
	global_store_dwordx4 v[204:205], v[78:81], off offset:16
	global_store_dwordx4 v[204:205], v[70:73], off offset:512
	global_store_dwordx4 v[204:205], v[66:69], off offset:528
	s_waitcnt vmcnt(16)
; #define PG8_BAR __builtin_amdgcn_s_barrier()
; template <class Epi, bool ALIGN_EPI = PG8_ALIGN, bool SP2 = PG8_SP2>
; __device__ __forceinline__ void gemm_phase(LAS unsigned char* lds, const Gemm g, const StaticOrder& S, const Epi& E) {
;     ...
;         if (!has_next) break;
; #pragma unroll
;         for (int a = 0; a < 2; ++a)
; #pragma unroll
;             for (int b = 0; b < 2; ++b)
; #pragma unroll
;                 for (int m = 0; m < 4; ++m)
; #pragma unroll
;                     for (int n = 0; n < 2; ++n) acc[a][b][m][n] = (f32x4){0.f, 0.f, 0.f, 0.f};
;         cur = nxt; cA = nA; cB = nB; ++ui;
;         if constexpr (ALIGN_EPI) { if (wr == 1) PG8_BAR; }
;     __device__ __forceinline__ void operator()(const f32x4 (&acc)[2][2][4][2], const pg8::Unit& u, int wr, int wc, int fr, int fq) const {
;     ...
;             for (int m = 0; m < 4; ++m)
; #pragma unroll
;                 for (int bj = 0; bj < 2; ++bj)
; #pragma unroll
;                     for (int n = 0; n < 2; ++n) *(f32x4*)(xo + (size_t)(row0 + ai * 128 + m * 16) * D + col0 + bj * 128 + n * 4) = xv[m][bj][n] + gv[bj][n] * acc[ai][bj][m][n];
	v_pk_fma_f32 v[64:65], v[64:65], v[146:147], v[176:177]
	v_pk_fma_f32 v[62:63], v[62:63], v[148:149], v[174:175]
	v_pk_fma_f32 v[60:61], v[60:61], v[142:143], v[180:181]
	v_pk_fma_f32 v[58:59], v[58:59], v[144:145], v[178:179]
	v_pk_fma_f32 v[44:45], v[44:45], v[138:139], v[188:189]
	v_pk_fma_f32 v[42:43], v[42:43], v[140:141], v[186:187]
	v_pk_fma_f32 v[40:41], v[40:41], v[134:135], v[184:185]
	v_pk_fma_f32 v[38:39], v[38:39], v[136:137], v[182:183]
	v_pk_fma_f32 v[56:57], v[56:57], v[146:147], v[208:209]
	v_pk_fma_f32 v[54:55], v[54:55], v[148:149], v[206:207]
	v_pk_fma_f32 v[52:53], v[52:53], v[142:143], v[212:213]
	v_pk_fma_f32 v[50:51], v[50:51], v[144:145], v[210:211]
	v_pk_fma_f32 v[32:33], v[32:33], v[138:139], v[220:221]
	v_pk_fma_f32 v[30:31], v[30:31], v[140:141], v[218:219]
	v_pk_fma_f32 v[28:29], v[28:29], v[134:135], v[216:217]
	v_pk_fma_f32 v[26:27], v[26:27], v[136:137], v[214:215]
	v_pk_fma_f32 v[48:49], v[48:49], v[146:147], v[224:225]
	v_pk_fma_f32 v[46:47], v[46:47], v[148:149], v[222:223]
	v_pk_fma_f32 v[36:37], v[36:37], v[142:143], v[228:229]
	v_pk_fma_f32 v[34:35], v[34:35], v[144:145], v[226:227]
	v_pk_fma_f32 v[24:25], v[24:25], v[138:139], v[232:233]
	v_pk_fma_f32 v[22:23], v[22:23], v[140:141], v[230:231]
	v_pk_fma_f32 v[12:13], v[12:13], v[134:135], v[236:237]
	v_pk_fma_f32 v[10:11], v[10:11], v[136:137], v[234:235]
	v_pk_fma_f32 v[20:21], v[20:21], v[146:147], v[240:241]
	v_pk_fma_f32 v[18:19], v[18:19], v[148:149], v[238:239]
	v_pk_fma_f32 v[16:17], v[16:17], v[142:143], v[244:245]
	v_pk_fma_f32 v[14:15], v[14:15], v[144:145], v[242:243]
	v_pk_fma_f32 v[8:9], v[8:9], v[138:139], v[196:197]
	v_pk_fma_f32 v[6:7], v[6:7], v[140:141], v[194:195]
	v_pk_fma_f32 v[4:5], v[4:5], v[134:135], v[166:167]
	v_pk_fma_f32 v[2:3], v[2:3], v[136:137], v[164:165]
	s_mov_b64 s[24:25], 0x80000
	v_lshl_add_u64 v[190:191], v[246:247], 0, s[24:25]
	global_store_dwordx4 v[190:191], v[62:65], off
	global_store_dwordx4 v[190:191], v[58:61], off offset:16
	global_store_dwordx4 v[190:191], v[42:45], off offset:512
	global_store_dwordx4 v[190:191], v[38:41], off offset:528
	s_mov_b64 s[24:25], 0x90000
	v_lshl_add_u64 v[204:205], v[246:247], 0, s[24:25]
	global_store_dwordx4 v[204:205], v[54:57], off
	global_store_dwordx4 v[204:205], v[50:53], off offset:16
	global_store_dwordx4 v[204:205], v[30:33], off offset:512
	global_store_dwordx4 v[204:205], v[26:29], off offset:528
	s_mov_b64 s[24:25], 0xa0000
	v_lshl_add_u64 v[190:191], v[246:247], 0, s[24:25]
	global_store_dwordx4 v[190:191], v[46:49], off
	global_store_dwordx4 v[190:191], v[34:37], off offset:16
	global_store_dwordx4 v[190:191], v[22:25], off offset:512
	global_store_dwordx4 v[190:191], v[10:13], off offset:528
	s_mov_b64 s[24:25], 0xb0000
	v_lshl_add_u64 v[204:205], v[246:247], 0, s[24:25]
	global_store_dwordx4 v[204:205], v[18:21], off
	global_store_dwordx4 v[204:205], v[14:17], off offset:16
	global_store_dwordx4 v[204:205], v[6:9], off offset:512
	global_store_dwordx4 v[204:205], v[2:5], off offset:528
	s_cbranch_vccnz .LBB0_574
	s_andn2_b64 vcc, exec, s[14:15]
	s_cbranch_vccnz .LBB0_573
	s_barrier
	s_branch .LBB0_573
